# grid barrier: non-leader workgroups spin on the cross-XCD generation word directly (one hop less per barrier); on top of SWA/mem LDS de-serialisation
# speedup vs baseline: 1.0036x; 1.0036x over previous
.LBB0_1498:
	s_or_b64 exec, exec, s[2:3]
	v_cvt_f32_u32_e32 v5, v3
	s_waitcnt vmcnt(0)
	v_readfirstlane_b32 s2, v4
	v_sub_u32_e32 v4, 0, v3
	v_rcp_iflag_f32_e32 v5, v5
	v_add_u32_e32 v6, s2, v1
	v_mul_f32_e32 v5, 0x4f7ffffe, v5
	v_cvt_u32_f32_e32 v5, v5
	v_mul_lo_u32 v1, v4, v5
	v_mul_hi_u32 v1, v5, v1
	v_add_u32_e32 v1, v5, v1
	v_mul_hi_u32 v1, v6, v1
	v_mul_lo_u32 v4, v1, v3
	v_sub_u32_e32 v4, v6, v4
	v_add_u32_e32 v5, 1, v1
	v_cmp_ge_u32_e32 vcc, v4, v3
	s_nop 1
	v_cndmask_b32_e32 v1, v1, v5, vcc
	v_sub_u32_e32 v5, v4, v3
	v_cndmask_b32_e32 v4, v4, v5, vcc
	v_add_u32_e32 v5, 1, v1
	v_cmp_ge_u32_e32 vcc, v4, v3
	v_add_u32_e32 v4, 1, v6
	s_nop 0
	v_cndmask_b32_e32 v1, v1, v5, vcc
	v_mul_lo_u32 v5, v3, v1
	v_add_u32_e32 v3, v5, v3
	v_cmp_ne_u32_e32 vcc, v4, v3
	s_and_saveexec_b64 s[2:3], vcc
	s_xor_b64 s[2:3], exec, s[2:3]
	s_cbranch_execz .LBB0_1513
	v_readlane_b32 s4, v243, 2
	v_readlane_b32 s5, v243, 3
	s_waitcnt lgkmcnt(0)
	s_nop 3
	global_load_dword v2, v0, s[4:5] sc1
	s_waitcnt vmcnt(0)
	v_cmp_eq_u32_e32 vcc, v2, v1
	s_and_saveexec_b64 s[4:5], vcc
	s_cbranch_execz .LBB0_1512
	s_mov_b32 s16, 1
	s_mov_b64 s[6:7], 0
	s_branch .LBB0_1502
